# scan producers: hand-over of next-step rows moved to the top of the following interval (loads stay in flight across the barrier)
# baseline (speedup 1.0000x reference)
; #define LAS __attribute__((address_space(3)))
; __device__ __forceinline__ void scan_unit_mfma(const TI ti, CArgs& a, int l, int u, bool ctx_out, unsigned char* ldsg) {
;     ...
;         const int p = w - 2, ch = hh * 64 + lane;
;         const bf16_t* RW = (const bf16_t*)(a.ws + WS_RW);
;         const bf16_t* DEC = (const bf16_t*)(a.ws + (d ? WS_DEC1 : WS_GV));
;         const bf16_t* AA = (const bf16_t*)(a.ws + (d ? WS_AA1 : WS_AA0));
;         const float* mu = a.in[16] + l * 3488;
;         const float mur = mu[ch], muk = mu[1024 + ch], muv = mu[2048 + ch], kkg = a.in[22][l * 1024 + ch], kag = a.in[23][l * 1024 + ch];
;         LAS unsigned char* buf = L + p * BUFB;
;         LAS bf16_t* AR = (LAS bf16_t*)(buf + O_AR); LAS bf16_t* BK = (LAS bf16_t*)(buf + O_BK); LAS bf16_t* BKT = (LAS bf16_t*)(buf + O_BKT); LAS bf16_t* VTT = (LAS bf16_t*)(buf + O_VTT);
;         LAS float* PC = (LAS float*)(buf + O_PC);
;         constexpr int NSTEP = (NCH / RING) * 4;
;         unsigned nxt[4][11], cur[4][11];
;     ...
;         SC2_LOAD(0);
.LBB0_304:
	s_mov_b32 s1, 0
	s_nop 0
	v_writelane_b32 v255, s1, 58
	v_readfirstlane_b32 s1, v178
	s_ashr_i32 s17, s1, 6
	s_ashr_i32 s16, s11, 5
	s_bfe_u32 s14, s11, 0x40001
	s_and_b32 s18, s11, 1
	s_cmp_gt_i32 s17, 1
	s_mov_b64 s[4:5], -1
	s_cbranch_scc0 .LBB0_319
	s_lshr_b32 s5, s1, 6
	s_add_i32 s27, s17, -2
	s_lshl_b32 s4, s14, 6
	s_load_dwordx2 s[62:63], s[74:75], 0x110
	s_cmp_eq_u32 s18, 0
	s_cselect_b64 s[60:61], -1, 0
	s_and_b64 s[6:7], s[60:61], exec
	s_mov_b32 s1, 0x8200000
	s_cselect_b32 s1, s1, 0x20e00000
	s_waitcnt lgkmcnt(0)
	s_add_u32 s34, s62, s1
	s_addc_u32 s35, s63, 0
	s_and_b64 s[6:7], s[60:61], exec
	s_load_dwordx2 s[6:7], s[74:75], 0x80
	s_load_dwordx4 s[76:79], s[74:75], 0xb0
	s_mov_b32 s1, 0x23200000
	s_cselect_b32 s1, s1, 0x25600000
	s_add_u32 s37, s62, s1
	s_addc_u32 s39, s63, 0
	v_or_b32_e32 v4, s4, v180
	s_waitcnt lgkmcnt(0)
	s_add_u32 s6, s6, s96
	s_addc_u32 s7, s7, s97
	v_lshlrev_b32_e32 v0, 2, v4
	v_lshl_add_u64 v[2:3], s[6:7], 0, v[0:1]
	v_add_co_u32_e32 v2, vcc, s93, v2
	v_readlane_b32 s1, v255, 57
	s_nop 0
	v_addc_co_u32_e32 v3, vcc, 0, v3, vcc
	global_load_dword v0, v0, s[6:7]
	s_nop 0
	global_load_dword v18, v[2:3], off offset:-4096
	global_load_dword v19, v[2:3], off
	v_or_b32_e32 v2, s1, v4
	v_ashrrev_i32_e32 v3, 31, v2
	v_lshlrev_b64 v[2:3], 2, v[2:3]
	v_lshl_add_u64 v[4:5], s[76:77], 0, v[2:3]
	v_lshl_add_u64 v[2:3], s[78:79], 0, v[2:3]
	s_mul_i32 s1, s27, 0x5100
	s_lshl_b32 s72, s16, 8
	global_load_dword v21, v[2:3], off
	s_add_i32 s62, s1, 0
	v_sub_co_u32_e64 v2, s[6:7], s17, 18
	s_addk_i32 s72, 0x4000
	s_lshl_b32 s73, s16, 11
	s_and_b64 s[6:7], s[6:7], exec
	v_readfirstlane_b32 s1, v2
	s_movk_i32 s90, 0x800
	s_cselect_b32 s1, s27, s1
	s_cselect_b32 s36, 0x100, s90
	s_cselect_b32 s33, s72, s73
	s_lshl_b32 s6, s14, 7
	v_readlane_b32 s3, v255, 54
	s_add_u32 s79, s3, s6
	v_readlane_b32 s3, v255, 56
	s_addc_u32 s81, s3, 0
	s_lshl_b32 s63, s1, 4
	s_not_b32 s1, s63
	s_add_i32 s7, s36, -1
	s_add_i32 s1, s36, s1
	s_and_b64 s[76:77], s[60:61], exec
	s_cselect_b32 s1, s63, s1
	s_add_i32 s76, s1, s33
	s_ashr_i32 s77, s76, 31
	s_mul_i32 s10, s76, 0x1c00
	s_mul_hi_i32 s3, s76, 0x1c00
	s_add_u32 s10, s79, s10
	s_addc_u32 s3, s81, s3
	s_add_u32 s92, s10, 0x800
	s_addc_u32 s93, s3, 0
	s_cmp_gt_i32 s1, 0
	s_cselect_b32 s10, 0xffffe400, 0
	s_cselect_b32 s3, -1, 0
	s_add_u32 s94, s92, s10
	s_addc_u32 s95, s93, s3
	s_cmp_lt_i32 s1, s7
	s_cselect_b32 s1, 0x1c00, 0
	s_add_u32 vcc_lo, s92, s1
	s_addc_u32 vcc_hi, s93, 0
	s_lshl_b64 s[76:77], s[76:77], 11
	s_add_u32 s1, s34, s76
	v_lshlrev_b32_e32 v22, 1, v180
	s_addc_u32 s3, s35, s77
	global_load_dword v20, v[4:5], off
	global_load_ushort v69, v22, s[94:95] offset:-2048
	global_load_ushort v66, v22, s[94:95]
	global_load_ushort v56, v22, s[94:95] offset:2048
	global_load_ushort v71, v22, s[92:93] offset:-2048
	global_load_ushort v70, v22, s[92:93]
	global_load_ushort v68, v22, s[92:93] offset:2048
	global_load_ushort v72, v22, vcc offset:-2048
	global_load_ushort v67, v22, vcc
	global_load_ushort v65, v22, vcc offset:2048
	s_add_u32 s92, s1, s6
	s_addc_u32 s93, s3, 0
	s_add_u32 s1, s37, s76
	s_addc_u32 s3, s39, s77
	s_add_u32 s76, s1, s6
	s_addc_u32 s77, s3, 0
	s_xor_b32 s3, s63, -2
	s_or_b32 s1, s63, 1
	s_add_i32 s3, s3, s36
	global_load_ushort v39, v22, s[92:93]
	global_load_ushort v51, v22, s[76:77]
	s_and_b64 s[76:77], s[60:61], exec
	s_cselect_b32 s1, s1, s3
	s_add_i32 s76, s1, s33
	s_ashr_i32 s77, s76, 31
	s_mul_i32 s10, s76, 0x1c00
	s_mul_hi_i32 s3, s76, 0x1c00
	s_add_u32 s10, s79, s10
	s_addc_u32 s3, s81, s3
	s_add_u32 s92, s10, 0x800
	s_addc_u32 s93, s3, 0
	s_cmp_gt_i32 s1, 0
	s_cselect_b32 s10, 0xffffe400, 0
	s_cselect_b32 s3, -1, 0
	s_add_u32 s94, s92, s10
	s_addc_u32 s95, s93, s3
	s_cmp_lt_i32 s1, s7
	s_cselect_b32 s1, 0x1c00, 0
	s_add_u32 vcc_lo, s92, s1
	s_addc_u32 vcc_hi, s93, 0
	s_lshl_b64 s[76:77], s[76:77], 11
	s_add_u32 s1, s34, s76
	s_addc_u32 s3, s35, s77
	global_load_ushort v52, v22, s[94:95] offset:-2048
	global_load_ushort v44, v22, s[94:95]
	global_load_ushort v35, v22, s[94:95] offset:2048
	global_load_ushort v64, v22, s[92:93] offset:-2048
	global_load_ushort v61, v22, s[92:93]
	global_load_ushort v55, v22, s[92:93] offset:2048
	global_load_ushort v62, v22, vcc offset:-2048
	global_load_ushort v47, v22, vcc
	global_load_ushort v40, v22, vcc offset:2048
	s_add_u32 s92, s1, s6
	s_addc_u32 s93, s3, 0
	s_add_u32 s1, s37, s76
	s_addc_u32 s3, s39, s77
	s_add_u32 s76, s1, s6
	s_addc_u32 s77, s3, 0
	s_xor_b32 s3, s63, -3
	s_or_b32 s1, s63, 2
	s_add_i32 s3, s3, s36
	global_load_ushort v27, v22, s[92:93]
	global_load_ushort v34, v22, s[76:77]
	s_and_b64 s[76:77], s[60:61], exec
	s_cselect_b32 s1, s1, s3
	s_add_i32 s76, s1, s33
	s_ashr_i32 s77, s76, 31
	s_mul_i32 s10, s76, 0x1c00
	s_mul_hi_i32 s3, s76, 0x1c00
	s_add_u32 s10, s79, s10
	s_addc_u32 s3, s81, s3
	s_add_u32 s92, s10, 0x800
	s_addc_u32 s93, s3, 0
	s_cmp_gt_i32 s1, 0
	s_cselect_b32 s10, 0xffffe400, 0
	s_cselect_b32 s3, -1, 0
	s_add_u32 s94, s92, s10
	s_addc_u32 s95, s93, s3
	s_cmp_lt_i32 s1, s7
	s_cselect_b32 s1, 0x1c00, 0
	s_add_u32 vcc_lo, s92, s1
	s_addc_u32 vcc_hi, s93, 0
	s_lshl_b64 s[76:77], s[76:77], 11
	s_add_u32 s1, s34, s76
	s_addc_u32 s3, s35, s77
	global_load_ushort v30, v22, s[94:95] offset:-2048
	global_load_ushort v25, v22, s[94:95]
	global_load_ushort v23, v22, s[94:95] offset:2048
	global_load_ushort v63, v22, s[92:93] offset:-2048
	global_load_ushort v57, v22, s[92:93]
	global_load_ushort v53, v22, s[92:93] offset:2048
	global_load_ushort v59, v22, vcc offset:-2048
	global_load_ushort v45, v22, vcc
	global_load_ushort v37, v22, vcc offset:2048
	s_add_u32 s92, s1, s6
; __device__ __forceinline__ void scan_unit_mfma(const TI ti, CArgs& a, int l, int u, bool ctx_out, unsigned char* ldsg) {
;     ...
;         SC2_LOAD(0);
;         float Lsum = 0.f, ePprev = 1.f;
;         for (int n = 0; n < NCH + RING; ++n) {
;             const int e = n - p - 1;
;             if (e >= 0 && (e % RING) < 4 && e / RING < NCH / RING) {
;                 const int k = 4 * (e / RING) + (e % RING);
; #pragma unroll
;                 for (int i4 = 0; i4 < 4; ++i4)
; #pragma unroll
;                     for (int x = 0; x < 11; ++x) cur[i4][x] = nxt[i4][x];
;                 if (k + 1 < NSTEP) SC2_LOAD(k + 1);
;                 const int C_ = p + RING * (k >> 2); SC2_CHUNK(C_, base_, Tn_, cc_, wy_); (void)wy_; (void)base_;
; #pragma unroll
;                 for (int i4 = 0; i4 < 4; ++i4) {
;                     const int t = 4 * (k & 3) + i4; const int tok = SC2_TOK(Tn_, cc_, t);
;                     Lsum = (t == 0) ? 0.f : Lsum; ePprev = (t == 0) ? 1.f : ePprev;
;                     const float mp_ = tok > 0 ? 0.5f : 0.f, mn_ = tok < Tn_ - 1 ? 0.5f : 0.f;
;                     const float xr = bf2f(cur[i4][1]), xk = bf2f(cur[i4][4]), xv = bf2f(cur[i4][7]);
;                     const float zr = xr + mur * ((mp_ * bf2f(cur[i4][0]) + mn_ * bf2f(cur[i4][2])) - xr);
;                     const float zk = xk + muk * ((mp_ * bf2f(cur[i4][3]) + mn_ * bf2f(cur[i4][5])) - xk);
;                     const float zv = xv + muv * ((mp_ * bf2f(cur[i4][6]) + mn_ * bf2f(cur[i4][8])) - xv);
;                     const float kkv = zk * kkg; const float ssq = wave_sum(kkv * kkv); const float kkn = kkv * rsqrtf(fmaxf(ssq, 1e-24f));
;                     const float ad = bf2f(cur[i4][10]); const float kd = zk * (1.f + (ad - 1.f) * kag);
;                     Lsum += bf2f(cur[i4][9]);
;                     const float eP = __expf(Lsum), eI = __expf(-Lsum);
;                     AR[t * 72 + lane] = f2bf(-kkn * ePprev); AR[(16 + t) * 72 + lane] = f2bf(zr * eP);
;                     const bf16_t bt = f2bf(kkn * ad * eI), kt = f2bf(kd * eI);
;                     BK[t * 72 + lane] = bt; BK[(16 + t) * 72 + lane] = kt;
;                     BKT[lane * 40 + t] = bt; BKT[lane * 40 + 16 + t] = kt;
;                     VTT[lane * 24 + t] = f2bf(zv);
;                     PC[lane] = eP;
;                     ePprev = eP;
;                 }
	s_addc_u32 s93, s3, 0
	s_add_u32 s1, s37, s76
	s_addc_u32 s3, s39, s77
	s_add_u32 s76, s1, s6
	s_addc_u32 s77, s3, 0
	s_xor_b32 s3, s63, -4
	s_or_b32 s1, s63, 3
	s_add_i32 s3, s3, s36
	global_load_ushort v41, v22, s[92:93]
	global_load_ushort v49, v22, s[76:77]
	s_and_b64 s[76:77], s[60:61], exec
	s_cselect_b32 s1, s1, s3
	s_add_i32 s76, s1, s33
	s_ashr_i32 s77, s76, 31
	s_mul_i32 s10, s76, 0x1c00
	s_mul_hi_i32 s3, s76, 0x1c00
	s_add_u32 s10, s79, s10
	s_addc_u32 s3, s81, s3
	s_add_u32 s92, s10, 0x800
	s_addc_u32 s93, s3, 0
	s_cmp_gt_i32 s1, 0
	s_cselect_b32 s10, 0xffffe400, 0
	s_cselect_b32 s3, -1, 0
	s_add_u32 s94, s92, s10
	s_addc_u32 s95, s93, s3
	s_cmp_lt_i32 s1, s7
	s_cselect_b32 s1, 0x1c00, 0
	s_add_u32 vcc_lo, s92, s1
	s_addc_u32 vcc_hi, s93, 0
	s_lshl_b64 s[76:77], s[76:77], 11
	s_add_u32 s1, s34, s76
	global_load_ushort v50, v22, s[94:95] offset:-2048
	global_load_ushort v42, v22, s[94:95]
	global_load_ushort v32, v22, s[94:95] offset:2048
	global_load_ushort v58, v22, s[92:93] offset:-2048
	global_load_ushort v54, v22, s[92:93]
	global_load_ushort v48, v22, s[92:93] offset:2048
	global_load_ushort v60, v22, vcc offset:-2048
	global_load_ushort v46, v22, vcc
	global_load_ushort v38, v22, vcc offset:2048
	s_addc_u32 s3, s35, s77
	s_add_u32 s92, s1, s6
	s_addc_u32 s93, s3, 0
	s_add_u32 s1, s37, s76
	s_addc_u32 s3, s39, s77
	s_add_u32 s6, s1, s6
	s_addc_u32 s7, s3, 0
	global_load_ushort v26, v22, s[92:93]
	global_load_ushort v43, v22, s[6:7]
	v_lshlrev_b32_e32 v3, 2, v80
	s_mul_i32 s1, s17, 0x4ec0
	v_add_u32_e32 v2, s62, v85
	v_add3_u32 v24, s62, v88, v3
	v_add_u32_e32 v3, s62, v90
	v_add_u32_e32 v28, s1, v95
	s_mul_i32 s1, s17, 0x50f8
	s_lshl_b32 s3, s17, 2
	s_mov_b32 s9, s67
	s_mov_b32 s76, 0
	s_sub_i32 s77, 0, s17
	s_sub_i32 s78, 1, s5
	s_sub_i32 s92, 1, s17
	v_add_u32_e32 v29, s1, v96
	s_add_i32 s93, s3, -8
	s_sub_i32 s94, 7, s3
	v_add_u32_e32 v31, s1, v97
	v_mov_b32_e32 v74, 1.0
	v_mov_b32_e32 v73, 0
	v_add_u32_e32 v33, v2, v86
	s_lshl_b32 s95, s4, 1
	v_add_u32_e32 v36, v3, v94
	s_branch .LBB0_308
.LBB0_306:
	s_mulk_i32 s1, 0xab
	s_bfe_u32 s1, s1, 0x6000a
	s_mul_i32 s1, s1, 6
	s_add_i32 s1, s1, s27
	s_lshl_b32 s4, s1, 4
	s_add_i32 s5, s4, 0xffffff00
	s_cmp_lt_i32 s1, 16
	s_mul_i32 s6, s3, 24
	s_cselect_b32 s1, 0x100, s90
	s_cselect_b32 s36, s4, s5
	s_mul_i32 s7, s3, 0xfffff280
	s_mul_i32 s33, s3, 0xffffffd0
	s_mulk_i32 s3, 0xffe8
	s_add_i32 s4, s1, -1
	s_add_i32 s5, s36, s94
	s_sub_i32 s1, s1, s36
	s_add_i32 s6, s93, s6
	s_add_i32 s5, s5, s3
	s_add_i32 s6, s6, s1
	s_add_i32 s3, s5, -3
	s_add_i32 s1, s6, 3
	s_and_b64 s[66:67], s[60:61], exec
	s_cselect_b32 s1, s3, s1
	s_cmp_eq_u32 s10, 0
	s_cselect_b64 s[66:67], -1, 0
	s_cmp_gt_i32 s1, 0
	v_cndmask_b32_e64 v73, v73, 0, s[66:67]
	v_cndmask_b32_e64 v74, v74, 1.0, s[66:67]
	s_cselect_b64 s[66:67], -1, 0
	s_cmp_lt_i32 s1, s4
	v_cndmask_b32_e64 v119, 0, 0.5, s[66:67]
	s_cselect_b64 s[66:67], -1, 0
	v_cndmask_b32_e64 v120, 0, 0.5, s[66:67]
	v_lshlrev_b32_e32 v67, 16, v67
	v_lshlrev_b32_e32 v66, 16, v66
	v_mul_f32_e32 v67, v120, v67
	v_lshlrev_b32_e32 v70, 16, v70
	v_fmac_f32_e32 v67, v119, v66
	v_sub_f32_e32 v66, v67, v70
	v_fmac_f32_e32 v70, v18, v66
	v_mul_f32_e32 v66, v20, v70
	v_mul_f32_e32 v67, v66, v66
	v_lshlrev_b32_e32 v72, 16, v72
	v_lshlrev_b32_e32 v69, 16, v69
	v_mov_b32_dpp v67, v67 quad_perm:[1,0,3,2] row_mask:0xf bank_mask:0xf bound_ctrl:1
	v_fmac_f32_e32 v67, v66, v66
	v_mul_f32_e32 v72, v120, v72
	v_lshlrev_b32_e32 v71, 16, v71
	v_add_f32_dpp v67, v67, v67 quad_perm:[2,3,0,1] row_mask:0xf bank_mask:0xf bound_ctrl:1
	v_fmac_f32_e32 v72, v119, v69
	v_sub_f32_e32 v69, v72, v71
	v_add_f32_dpp v67, v67, v67 row_half_mirror row_mask:0xf bank_mask:0xf bound_ctrl:1
	v_fmac_f32_e32 v71, v0, v69
	v_lshlrev_b32_e32 v65, 16, v65
	v_add_f32_dpp v67, v67, v67 row_mirror row_mask:0xf bank_mask:0xf bound_ctrl:1
	v_lshlrev_b32_e32 v56, 16, v56
	v_readlane_b32 s3, v67, 16
	v_readlane_b32 s36, v67, 48
	v_readlane_b32 s1, v67, 0
	v_readlane_b32 s10, v67, 32
	v_mov_b32_e32 v67, s3
	v_mov_b32_e32 v69, s36
	v_add_f32_e32 v67, s1, v67
	v_add_f32_e32 v69, s10, v69
	v_add_f32_e32 v67, v67, v69
	v_max_f32_e32 v67, 0x179abe15, v67
	v_rsq_f32_e32 v67, v67
	v_mul_f32_e32 v65, v120, v65
	v_lshlrev_b32_e32 v68, 16, v68
	v_fmac_f32_e32 v65, v119, v56
	v_lshlrev_b32_e32 v39, 16, v39
	v_sub_f32_e32 v56, v65, v68
	v_add_f32_e32 v39, v73, v39
	v_fmac_f32_e32 v68, v19, v56
	v_mul_f32_e32 v56, v66, v67
	v_mul_f32_e32 v66, 0x3fb8aa3b, v39
	v_mul_f32_e32 v67, 0xbfb8aa3b, v39
	v_lshlrev_b32_e32 v51, 16, v51
	v_exp_f32_e32 v66, v66
	v_exp_f32_e32 v67, v67
	v_add_f32_e32 v65, -1.0, v51
	v_fma_f32 v65, v21, v65, 1.0
	v_mul_f32_e64 v69, v74, -v56
	s_add_i32 s1, s5, -2
	s_add_i32 s3, s6, 2
	v_mul_f32_e32 v65, v65, v70
	v_cvt_pk_bf16_f32 v69, v69, s0
	v_add_u32_e32 v70, s7, v28
	v_mul_f32_e32 v51, v56, v51
	s_and_b64 s[66:67], s[60:61], exec
	ds_write_b16 v70, v69
	v_mul_f32_e32 v69, v66, v71
	v_mul_f32_e32 v51, v67, v51
	v_mul_f32_e32 v56, v67, v65
	s_cselect_b32 s1, s1, s3
	v_cvt_pk_bf16_f32 v69, v69, s0
	v_cvt_pk_bf16_f32 v51, v51, s0
	v_cvt_pk_bf16_f32 v56, v56, s0
	v_add_u32_e32 v65, s33, v31
	s_cmp_gt_i32 s1, 0
	ds_write_b16 v70, v69 offset:2304
	ds_write_b16 v70, v51 offset:4608
	ds_write_b16 v70, v56 offset:6912
	ds_write_b16 v65, v51
	ds_write_b16 v65, v56 offset:32
	v_cvt_pk_bf16_f32 v51, v68, s0
	v_add_u32_e32 v56, s33, v29
	s_cselect_b64 s[66:67], -1, 0
	s_cmp_lt_i32 s1, s4
	ds_write_b16 v56, v51
	v_cndmask_b32_e64 v51, 0, 0.5, s[66:67]
	s_cselect_b64 s[66:67], -1, 0
	v_cndmask_b32_e64 v67, 0, 0.5, s[66:67]
	v_lshlrev_b32_e32 v47, 16, v47
	v_lshlrev_b32_e32 v44, 16, v44
	v_mul_f32_e32 v47, v67, v47
; __device__ __forceinline__ float bf2f(unsigned v) { return __uint_as_float(v << 16); }
; __device__ __forceinline__ bf16_t f2bf(float f) { return (bf16_t)(pkbf(f, 0.f) & 0xffffu); }
; __device__ __forceinline__ void scan_unit_mfma(const TI ti, CArgs& a, int l, int u, bool ctx_out, unsigned char* ldsg) {
;     ...
;                 for (int i4 = 0; i4 < 4; ++i4) {
;                     const int t = 4 * (k & 3) + i4; const int tok = SC2_TOK(Tn_, cc_, t);
;                     Lsum = (t == 0) ? 0.f : Lsum; ePprev = (t == 0) ? 1.f : ePprev;
;                     const float mp_ = tok > 0 ? 0.5f : 0.f, mn_ = tok < Tn_ - 1 ? 0.5f : 0.f;
;                     const float xr = bf2f(cur[i4][1]), xk = bf2f(cur[i4][4]), xv = bf2f(cur[i4][7]);
;                     const float zr = xr + mur * ((mp_ * bf2f(cur[i4][0]) + mn_ * bf2f(cur[i4][2])) - xr);
;                     const float zk = xk + muk * ((mp_ * bf2f(cur[i4][3]) + mn_ * bf2f(cur[i4][5])) - xk);
;                     const float zv = xv + muv * ((mp_ * bf2f(cur[i4][6]) + mn_ * bf2f(cur[i4][8])) - xv);
;                     const float kkv = zk * kkg; const float ssq = wave_sum(kkv * kkv); const float kkn = kkv * rsqrtf(fmaxf(ssq, 1e-24f));
;                     const float ad = bf2f(cur[i4][10]); const float kd = zk * (1.f + (ad - 1.f) * kag);
;                     Lsum += bf2f(cur[i4][9]);
;                     const float eP = __expf(Lsum), eI = __expf(-Lsum);
;                     AR[t * 72 + lane] = f2bf(-kkn * ePprev); AR[(16 + t) * 72 + lane] = f2bf(zr * eP);
;                     const bf16_t bt = f2bf(kkn * ad * eI), kt = f2bf(kd * eI);
;                     BK[t * 72 + lane] = bt; BK[(16 + t) * 72 + lane] = kt;
;                     BKT[lane * 40 + t] = bt; BKT[lane * 40 + 16 + t] = kt;
;                     VTT[lane * 24 + t] = f2bf(zv);
;                     PC[lane] = eP;
;                     ePprev = eP;
	v_lshlrev_b32_e32 v61, 16, v61
	v_fmac_f32_e32 v47, v51, v44
	v_sub_f32_e32 v44, v47, v61
	v_fmac_f32_e32 v61, v18, v44
	v_mul_f32_e32 v44, v20, v61
	v_mul_f32_e32 v47, v44, v44
	v_lshlrev_b32_e32 v62, 16, v62
	v_lshlrev_b32_e32 v52, 16, v52
	v_mov_b32_dpp v47, v47 quad_perm:[1,0,3,2] row_mask:0xf bank_mask:0xf bound_ctrl:1
	v_fmac_f32_e32 v47, v44, v44
	v_mul_f32_e32 v62, v67, v62
	v_lshlrev_b32_e32 v64, 16, v64
	v_add_f32_dpp v47, v47, v47 quad_perm:[2,3,0,1] row_mask:0xf bank_mask:0xf bound_ctrl:1
	v_fmac_f32_e32 v62, v51, v52
	v_sub_f32_e32 v52, v62, v64
	v_add_f32_dpp v47, v47, v47 row_half_mirror row_mask:0xf bank_mask:0xf bound_ctrl:1
	v_fmac_f32_e32 v64, v0, v52
	v_lshlrev_b32_e32 v40, 16, v40
	v_add_f32_dpp v47, v47, v47 row_mirror row_mask:0xf bank_mask:0xf bound_ctrl:1
	v_lshlrev_b32_e32 v35, 16, v35
	v_readlane_b32 s3, v47, 16
	v_readlane_b32 s10, v47, 48
	v_readlane_b32 s1, v47, 0
	v_readlane_b32 s7, v47, 32
	v_mov_b32_e32 v47, s3
	v_mov_b32_e32 v52, s10
	v_add_f32_e32 v47, s1, v47
	v_add_f32_e32 v52, s7, v52
	v_add_f32_e32 v47, v47, v52
	v_max_f32_e32 v47, 0x179abe15, v47
	v_rsq_f32_e32 v47, v47
	v_mul_f32_e32 v40, v67, v40
	v_lshlrev_b32_e32 v55, 16, v55
	v_fmac_f32_e32 v40, v51, v35
	v_lshlrev_b32_e32 v27, 16, v27
	v_sub_f32_e32 v35, v40, v55
	v_add_f32_e32 v27, v39, v27
	v_fmac_f32_e32 v55, v19, v35
	v_mul_f32_e32 v35, v44, v47
	v_mul_f32_e32 v39, 0x3fb8aa3b, v27
	v_mul_f32_e32 v44, 0xbfb8aa3b, v27
	v_exp_f32_e32 v39, v39
	v_exp_f32_e32 v44, v44
	v_lshlrev_b32_e32 v34, 16, v34
	v_add_f32_e32 v40, -1.0, v34
	v_mul_f32_e64 v47, v66, -v35
	s_add_i32 s1, s5, -1
	s_add_i32 s3, s6, 1
	v_fma_f32 v40, v21, v40, 1.0
	v_cvt_pk_bf16_f32 v47, v47, s0
	v_mul_f32_e32 v34, v35, v34
	s_and_b64 s[66:67], s[60:61], exec
	v_mul_f32_e32 v40, v40, v61
	ds_write_b16 v70, v47 offset:144
	v_mul_f32_e32 v47, v39, v64
	v_mul_f32_e32 v34, v44, v34
	s_cselect_b32 s1, s1, s3
	v_cvt_pk_bf16_f32 v47, v47, s0
	v_cvt_pk_bf16_f32 v34, v34, s0
	v_mul_f32_e32 v35, v44, v40
	s_cmp_gt_i32 s1, 0
	ds_write_b16 v70, v47 offset:2448
	v_cvt_pk_bf16_f32 v35, v35, s0
	ds_write_b16 v70, v34 offset:4752
	ds_write_b16 v70, v35 offset:7056
	ds_write_b16 v65, v34 offset:2
	ds_write_b16 v65, v35 offset:34
	v_cvt_pk_bf16_f32 v34, v55, s0
	s_cselect_b64 s[66:67], -1, 0
	s_cmp_lt_i32 s1, s4
	ds_write_b16 v56, v34 offset:2
	v_cndmask_b32_e64 v34, 0, 0.5, s[66:67]
	s_cselect_b64 s[66:67], -1, 0
	v_cndmask_b32_e64 v35, 0, 0.5, s[66:67]
	v_lshlrev_b32_e32 v51, 16, v59
	v_lshlrev_b32_e32 v30, 16, v30
	v_mul_f32_e32 v51, v35, v51
	v_lshlrev_b32_e32 v40, 16, v63
	v_fmac_f32_e32 v51, v34, v30
	v_sub_f32_e32 v30, v51, v40
	v_fmac_f32_e32 v40, v0, v30
	v_lshlrev_b32_e32 v30, 16, v45
	v_lshlrev_b32_e32 v25, 16, v25
	v_mul_f32_e32 v30, v35, v30
	v_lshlrev_b32_e32 v44, 16, v57
	v_fmac_f32_e32 v30, v34, v25
	v_sub_f32_e32 v25, v30, v44
	v_fmac_f32_e32 v44, v18, v25
	v_lshlrev_b32_e32 v25, 16, v37
	v_mul_f32_e32 v30, v20, v44
	v_mul_f32_e32 v25, v35, v25
	v_mul_f32_e32 v35, v30, v30
	v_lshlrev_b32_e32 v23, 16, v23
	v_lshlrev_b32_e32 v47, 16, v53
	v_mov_b32_dpp v35, v35 quad_perm:[1,0,3,2] row_mask:0xf bank_mask:0xf bound_ctrl:1
	v_fmac_f32_e32 v35, v30, v30
	v_fmac_f32_e32 v25, v34, v23
	v_lshlrev_b32_e32 v34, 16, v41
	v_add_f32_dpp v35, v35, v35 quad_perm:[2,3,0,1] row_mask:0xf bank_mask:0xf bound_ctrl:1
	v_sub_f32_e32 v23, v25, v47
	v_add_f32_e32 v27, v27, v34
	v_add_f32_dpp v35, v35, v35 row_half_mirror row_mask:0xf bank_mask:0xf bound_ctrl:1
	v_fmac_f32_e32 v47, v19, v23
	v_mul_f32_e32 v34, 0x3fb8aa3b, v27
	v_add_f32_dpp v35, v35, v35 row_mirror row_mask:0xf bank_mask:0xf bound_ctrl:1
	v_lshlrev_b32_e32 v25, 16, v49
; __device__ __forceinline__ float bf2f(unsigned v) { return __uint_as_float(v << 16); }
; __device__ __forceinline__ bf16_t f2bf(float f) { return (bf16_t)(pkbf(f, 0.f) & 0xffffu); }
; __device__ __forceinline__ void scan_unit_mfma(const TI ti, CArgs& a, int l, int u, bool ctx_out, unsigned char* ldsg) {
;     ...
;                 for (int i4 = 0; i4 < 4; ++i4) {
;                     const int t = 4 * (k & 3) + i4; const int tok = SC2_TOK(Tn_, cc_, t);
;                     Lsum = (t == 0) ? 0.f : Lsum; ePprev = (t == 0) ? 1.f : ePprev;
;                     const float mp_ = tok > 0 ? 0.5f : 0.f, mn_ = tok < Tn_ - 1 ? 0.5f : 0.f;
;                     const float xr = bf2f(cur[i4][1]), xk = bf2f(cur[i4][4]), xv = bf2f(cur[i4][7]);
;                     const float zr = xr + mur * ((mp_ * bf2f(cur[i4][0]) + mn_ * bf2f(cur[i4][2])) - xr);
;                     const float zk = xk + muk * ((mp_ * bf2f(cur[i4][3]) + mn_ * bf2f(cur[i4][5])) - xk);
;                     const float zv = xv + muv * ((mp_ * bf2f(cur[i4][6]) + mn_ * bf2f(cur[i4][8])) - xv);
;                     const float kkv = zk * kkg; const float ssq = wave_sum(kkv * kkv); const float kkn = kkv * rsqrtf(fmaxf(ssq, 1e-24f));
;                     const float ad = bf2f(cur[i4][10]); const float kd = zk * (1.f + (ad - 1.f) * kag);
;                     Lsum += bf2f(cur[i4][9]);
;                     const float eP = __expf(Lsum), eI = __expf(-Lsum);
;                     AR[t * 72 + lane] = f2bf(-kkn * ePprev); AR[(16 + t) * 72 + lane] = f2bf(zr * eP);
;                     const bf16_t bt = f2bf(kkn * ad * eI), kt = f2bf(kd * eI);
;                     BK[t * 72 + lane] = bt; BK[(16 + t) * 72 + lane] = kt;
;                     BKT[lane * 40 + t] = bt; BKT[lane * 40 + 16 + t] = kt;
;                     VTT[lane * 24 + t] = f2bf(zv);
;                     PC[lane] = eP;
;                     ePprev = eP;
;                 }
	v_readlane_b32 s3, v35, 16
	v_readlane_b32 s10, v35, 48
	v_readlane_b32 s1, v35, 0
	v_readlane_b32 s7, v35, 32
	v_mov_b32_e32 v35, s3
	v_mov_b32_e32 v37, s10
	v_add_f32_e32 v35, s1, v35
	v_add_f32_e32 v37, s7, v37
	v_add_f32_e32 v35, v35, v37
	v_max_f32_e32 v35, 0x179abe15, v35
	v_rsq_f32_e32 v35, v35
	v_exp_f32_e32 v34, v34
	s_and_b64 s[66:67], s[60:61], exec
	s_cselect_b32 s1, s5, s6
	v_mul_f32_e32 v23, v30, v35
	v_mul_f32_e32 v35, 0xbfb8aa3b, v27
	v_exp_f32_e32 v35, v35
	v_add_f32_e32 v30, -1.0, v25
	v_fma_f32 v30, v21, v30, 1.0
	v_mul_f32_e64 v37, v39, -v23
	v_mul_f32_e32 v30, v30, v44
	v_cvt_pk_bf16_f32 v37, v37, s0
	v_mul_f32_e32 v23, v23, v25
	s_cmp_gt_i32 s1, 0
	ds_write_b16 v70, v37 offset:288
	v_mul_f32_e32 v37, v34, v40
	v_mul_f32_e32 v23, v35, v23
	v_mul_f32_e32 v25, v35, v30
	s_cselect_b64 s[6:7], -1, 0
	s_cmp_lt_i32 s1, s4
	v_cvt_pk_bf16_f32 v37, v37, s0
	v_cvt_pk_bf16_f32 v23, v23, s0
	v_cvt_pk_bf16_f32 v25, v25, s0
	s_cselect_b64 s[4:5], -1, 0
	ds_write_b16 v70, v37 offset:2592
	ds_write_b16 v70, v23 offset:4896
	ds_write_b16 v70, v25 offset:7200
	ds_write_b16 v65, v23 offset:4
	ds_write_b16 v65, v25 offset:36
	v_cvt_pk_bf16_f32 v23, v47, s0
	v_cndmask_b32_e64 v25, 0, 0.5, s[4:5]
	v_lshlrev_b32_e32 v40, 16, v60
	ds_write_b16 v56, v23 offset:4
	v_cndmask_b32_e64 v23, 0, 0.5, s[6:7]
	v_lshlrev_b32_e32 v39, 16, v50
	v_mul_f32_e32 v40, v25, v40
	v_lshlrev_b32_e32 v30, 16, v58
	v_fmac_f32_e32 v40, v23, v39
	v_sub_f32_e32 v39, v40, v30
	v_lshlrev_b32_e32 v40, 16, v46
	v_fmac_f32_e32 v30, v0, v39
	v_lshlrev_b32_e32 v39, 16, v42
	v_mul_f32_e32 v40, v25, v40
	v_lshlrev_b32_e32 v35, 16, v54
	v_fmac_f32_e32 v40, v23, v39
	v_sub_f32_e32 v39, v40, v35
	v_fmac_f32_e32 v35, v18, v39
	v_lshlrev_b32_e32 v38, 16, v38
	v_mul_f32_e32 v25, v25, v38
	v_mul_f32_e32 v38, v20, v35
	v_mul_f32_e32 v39, v38, v38
	v_lshlrev_b32_e32 v26, 16, v26
	v_add_f32_e32 v73, v27, v26
	v_mov_b32_dpp v39, v39 quad_perm:[1,0,3,2] row_mask:0xf bank_mask:0xf bound_ctrl:1
	v_fmac_f32_e32 v39, v38, v38
	v_lshlrev_b32_e32 v32, 16, v32
	v_mul_f32_e32 v26, 0x3fb8aa3b, v73
	v_add_f32_dpp v39, v39, v39 quad_perm:[2,3,0,1] row_mask:0xf bank_mask:0xf bound_ctrl:1
	v_lshlrev_b32_e32 v37, 16, v48
	v_fmac_f32_e32 v25, v23, v32
	v_add_f32_dpp v39, v39, v39 row_half_mirror row_mask:0xf bank_mask:0xf bound_ctrl:1
	v_exp_f32_e32 v74, v26
	v_mul_f32_e32 v26, 0xbfb8aa3b, v73
	v_add_f32_dpp v39, v39, v39 row_mirror row_mask:0xf bank_mask:0xf bound_ctrl:1
	v_sub_f32_e32 v23, v25, v37
	v_readlane_b32 s3, v39, 16
	v_readlane_b32 s5, v39, 48
	v_readlane_b32 s1, v39, 0
	v_readlane_b32 s4, v39, 32
	v_mov_b32_e32 v39, s3
	v_mov_b32_e32 v40, s5
	v_add_f32_e32 v39, s1, v39
	v_add_f32_e32 v40, s4, v40
	v_add_f32_e32 v39, v39, v40
	v_max_f32_e32 v39, 0x179abe15, v39
	v_rsq_f32_e32 v39, v39
	v_exp_f32_e32 v26, v26
	v_fmac_f32_e32 v37, v19, v23
	v_lshlrev_b32_e32 v25, 16, v43
	v_mul_f32_e32 v23, v38, v39
	v_add_f32_e32 v32, -1.0, v25
	v_mul_f32_e64 v27, v34, -v23
	v_fma_f32 v32, v21, v32, 1.0
	v_cvt_pk_bf16_f32 v27, v27, s0
	v_mul_f32_e32 v23, v23, v25
	v_mul_f32_e32 v32, v32, v35
	ds_write_b16 v70, v27 offset:432
	v_mul_f32_e32 v27, v74, v30
	v_mul_f32_e32 v23, v26, v23
	v_cvt_pk_bf16_f32 v27, v27, s0
	v_cvt_pk_bf16_f32 v23, v23, s0
	v_mul_f32_e32 v25, v26, v32
	ds_write_b16 v70, v27 offset:2736
	v_cvt_pk_bf16_f32 v25, v25, s0
	ds_write_b16 v70, v23 offset:5040
	ds_write_b16 v70, v25 offset:7344
	ds_write_b16 v65, v23 offset:6
	ds_write_b16 v65, v25 offset:38
	v_cvt_pk_bf16_f32 v23, v37, s0
	ds_write_b16 v56, v23 offset:6
	ds_write_b32 v36, v74 offset:17408
	s_mov_b32 s1, 1
	s_nop 0
	v_writelane_b32 v255, s1, 58

; __device__ __forceinline__ void scan_unit_mfma(const TI ti, CArgs& a, int l, int u, bool ctx_out, unsigned char* ldsg) {
;     ...
;         for (int n = 0; n < NCH + RING; ++n) {
;             const int e = n - p - 1;
;             if (e >= 0 && (e % RING) < 4 && e / RING < NCH / RING) {
;                 const int k = 4 * (e / RING) + (e % RING);
; #pragma unroll
;                 for (int i4 = 0; i4 < 4; ++i4)
; #pragma unroll
;                     for (int x = 0; x < 11; ++x) cur[i4][x] = nxt[i4][x];
;                 if (k + 1 < NSTEP) SC2_LOAD(k + 1);
.LBB0_308:
	v_readlane_b32 s1, v255, 58
	s_nop 3
	s_cmp_eq_u32 s1, 0
	s_cbranch_scc1 .Lsc_nocopy
	s_waitcnt vmcnt(0)
	v_mov_b32_e32 v43, v118
	v_mov_b32_e32 v26, v117
	v_mov_b32_e32 v38, v116
	v_mov_b32_e32 v48, v114
	v_mov_b32_e32 v32, v113
	v_mov_b32_e32 v46, v115
	v_mov_b32_e32 v54, v111
	v_mov_b32_e32 v42, v110
	v_mov_b32_e32 v60, v112
	v_mov_b32_e32 v58, v109
	v_mov_b32_e32 v50, v108
	v_mov_b32_e32 v49, v107
	v_mov_b32_e32 v41, v106
	v_mov_b32_e32 v37, v105
	v_mov_b32_e32 v53, v104
	v_mov_b32_e32 v23, v99
	v_mov_b32_e32 v45, v103
	v_mov_b32_e32 v57, v102
	v_mov_b32_e32 v25, v98
	v_mov_b32_e32 v59, v101
	v_mov_b32_e32 v63, v100
	v_mov_b32_e32 v30, v83
	v_mov_b32_e32 v34, v82
	v_mov_b32_e32 v27, v79
	v_mov_b32_e32 v40, v78
	v_mov_b32_e32 v55, v77
	v_mov_b32_e32 v35, v17
	v_mov_b32_e32 v47, v76
	v_mov_b32_e32 v61, v75
	v_mov_b32_e32 v44, v14
	v_mov_b32_e32 v62, v16
	v_mov_b32_e32 v64, v15
	v_mov_b32_e32 v52, v13
	v_mov_b32_e32 v51, v12
	v_mov_b32_e32 v39, v11
	v_mov_b32_e32 v65, v10
	v_mov_b32_e32 v68, v8
	v_mov_b32_e32 v56, v7
	v_mov_b32_e32 v67, v9
	v_mov_b32_e32 v70, v5
	v_mov_b32_e32 v66, v4
	v_mov_b32_e32 v72, v6
	v_mov_b32_e32 v71, v3
	v_mov_b32_e32 v69, v2
	s_mov_b32 s1, 0
	s_nop 0
	v_writelane_b32 v255, s1, 58
